# v66 + hipcc's per-trip s_waitcnt vmcnt(0) at the top of the merge K-loop removed (counted waits cover the ring)
# speedup vs baseline: 1.0073x; 1.0009x over previous
; #define PG8_WAIT_V(n) asm volatile("s_waitcnt vmcnt(" #n ")" ::: "memory")
; template <class Epi, bool ALIGN_EPI, bool SP2, class Hook>
; __device__ __forceinline__ void gemm_phase(LAS unsigned char* lds, const Gemm g, const StaticOrder& S, const Epi& E, Acc& acc, const bool fresh, const Hook& H, const int wave_id) {
;     ...
;         for (int t = t0; t < nt; t += 2) {
;             const bool last = (t == nt - 2);
;             const Src a1 = cA + (size_t)(t + 1) * kstep;
;             const Src a2 = last ? nA : cA + (size_t)(t + 2) * kstep, b2 = last ? nB : cB + (size_t)(t + 2) * kstep;
;             const Src a3 = a2 + kstep, b3 = b2 + kstep;
;             if (last && has_next) H(nxt);
;             if constexpr (SP2) {
;             PG8_TRIP_SP2(PG8_WAIT_V(8));
.LBB0_1029:
.LBB0_1030:
	v_add_u32_e32 v0, 0x10000, v230
	ds_read_b128 v[130:133], v0
	ds_read_b128 v[134:137], v0 offset:1024
	ds_read_b128 v[138:141], v0 offset:2048
	ds_read_b128 v[142:145], v0 offset:3072
	v_add_u32_e32 v0, 0x14000, v230
	ds_read_b128 v[146:149], v0
	ds_read_b128 v[150:153], v0 offset:1024
	ds_read_b128 v[154:157], v0 offset:2048
	ds_read_b128 v[158:161], v0 offset:3072
	s_lshl_b32 s55, s20, 7
	s_add_i32 s18, s73, s55
	s_and_b64 s[12:13], s[16:17], exec
	s_cselect_b32 s13, s31, s9
	s_cselect_b32 s12, s30, s8
	s_cselect_b32 s15, s35, s11
	s_cselect_b32 s14, s34, s10
	s_cselect_b32 s56, s68, s18
	s_add_i32 s21, s74, s55
	s_and_b64 s[16:17], s[16:17], exec
	s_cselect_b32 s54, s69, s21
	s_cselect_b32 s17, s51, s77
	s_cselect_b32 s16, s50, s76
	s_cselect_b32 s19, s53, s7
	s_cselect_b32 s18, s52, s6
	s_or_b32 s21, s56, 0x80
	s_or_b32 s57, s54, 0x80
	s_add_i32 s55, s55, s75
	s_mov_b32 m0, s45
	ds_read_b128 v[162:165], v231
	ds_read_b128 v[166:169], v231 offset:1024
	ds_read_b128 v[170:173], v231 offset:2048
	ds_read_b128 v[174:177], v231 offset:3072
	ds_read_b128 v[178:181], v231 offset:4096
	ds_read_b128 v[182:185], v231 offset:5120
	ds_read_b128 v[186:189], v231 offset:6144
	ds_read_b128 v[190:193], v231 offset:7168
	buffer_load_dwordx4 v199, s[8:11], s55 offen lds
	s_mov_b32 m0, s46
	s_nop 0
	buffer_load_dwordx4 v228, s[8:11], s55 offen lds
	s_waitcnt vmcnt(8)
	s_waitcnt lgkmcnt(0)
	s_setprio 1
	s_barrier
	v_mfma_f32_16x16x32_bf16 v[126:129], v[130:133], v[162:165], v[126:129]
	v_mfma_f32_16x16x32_bf16 v[122:125], v[138:141], v[162:165], v[122:125]
	v_mfma_f32_16x16x32_bf16 v[118:121], v[130:133], v[170:173], v[118:121]
	v_mfma_f32_16x16x32_bf16 v[114:117], v[138:141], v[170:173], v[114:117]
	v_mfma_f32_16x16x32_bf16 v[110:113], v[130:133], v[178:181], v[110:113]
	v_mfma_f32_16x16x32_bf16 v[106:109], v[138:141], v[178:181], v[106:109]
	v_mfma_f32_16x16x32_bf16 v[102:105], v[130:133], v[186:189], v[102:105]
	v_mfma_f32_16x16x32_bf16 v[98:101], v[138:141], v[186:189], v[98:101]
	v_mfma_f32_16x16x32_bf16 v[126:129], v[134:137], v[166:169], v[126:129]
	v_mfma_f32_16x16x32_bf16 v[122:125], v[142:145], v[166:169], v[122:125]
	v_mfma_f32_16x16x32_bf16 v[118:121], v[134:137], v[174:177], v[118:121]
	v_mfma_f32_16x16x32_bf16 v[114:117], v[142:145], v[174:177], v[114:117]
	v_mfma_f32_16x16x32_bf16 v[110:113], v[134:137], v[182:185], v[110:113]
	v_mfma_f32_16x16x32_bf16 v[106:109], v[142:145], v[182:185], v[106:109]
	v_mfma_f32_16x16x32_bf16 v[102:105], v[134:137], v[190:193], v[102:105]
	v_mfma_f32_16x16x32_bf16 v[98:101], v[142:145], v[190:193], v[98:101]
	v_mfma_f32_16x16x32_bf16 v[94:97], v[146:149], v[162:165], v[94:97]
	v_mfma_f32_16x16x32_bf16 v[90:93], v[154:157], v[162:165], v[90:93]
	v_mfma_f32_16x16x32_bf16 v[86:89], v[146:149], v[170:173], v[86:89]
	v_mfma_f32_16x16x32_bf16 v[82:85], v[154:157], v[170:173], v[82:85]
	v_mfma_f32_16x16x32_bf16 v[78:81], v[146:149], v[178:181], v[78:81]
	v_mfma_f32_16x16x32_bf16 v[74:77], v[154:157], v[178:181], v[74:77]
	v_mfma_f32_16x16x32_bf16 v[70:73], v[146:149], v[186:189], v[70:73]
	v_mfma_f32_16x16x32_bf16 v[66:69], v[154:157], v[186:189], v[66:69]
	v_mfma_f32_16x16x32_bf16 v[94:97], v[150:153], v[166:169], v[94:97]
	v_mfma_f32_16x16x32_bf16 v[90:93], v[158:161], v[166:169], v[90:93]
	v_mfma_f32_16x16x32_bf16 v[86:89], v[150:153], v[174:177], v[86:89]
	v_mfma_f32_16x16x32_bf16 v[82:85], v[158:161], v[174:177], v[82:85]
	v_mfma_f32_16x16x32_bf16 v[78:81], v[150:153], v[182:185], v[78:81]
	v_mfma_f32_16x16x32_bf16 v[74:77], v[158:161], v[182:185], v[74:77]
	v_mfma_f32_16x16x32_bf16 v[70:73], v[150:153], v[190:193], v[70:73]
	v_mfma_f32_16x16x32_bf16 v[66:69], v[158:161], v[190:193], v[66:69]
	s_barrier
	s_setprio 0
	s_mov_b32 m0, s92
	ds_read_b128 v[162:165], v231 offset:16384
	ds_read_b128 v[166:169], v231 offset:17408
	ds_read_b128 v[170:173], v231 offset:18432
	ds_read_b128 v[174:177], v231 offset:19456
	ds_read_b128 v[178:181], v231 offset:20480
	ds_read_b128 v[182:185], v231 offset:21504
	ds_read_b128 v[186:189], v231 offset:22528
	ds_read_b128 v[190:193], v231 offset:23552
	buffer_load_dwordx4 v227, s[16:19], s54 offen lds
	s_mov_b32 m0, s93
	s_add_i32 s55, s54, 0x20000
	buffer_load_dwordx4 v229, s[16:19], s54 offen lds
	s_mov_b32 m0, s94
	s_nop 0
	buffer_load_dwordx4 v227, s[16:19], s55 offen lds
	s_mov_b32 m0, s95
	s_nop 0
	buffer_load_dwordx4 v229, s[16:19], s55 offen lds
	s_mov_b32 m0, s44
	s_nop 0
	buffer_load_dwordx4 v199, s[12:15], s56 offen lds
	s_mov_b32 m0, s36
	s_nop 0
	buffer_load_dwordx4 v228, s[12:15], s56 offen lds
	s_waitcnt vmcnt(8)
	s_waitcnt lgkmcnt(0)
	s_setprio 1
	s_barrier
	v_mfma_f32_16x16x32_bf16 v[62:65], v[130:133], v[162:165], v[62:65]
	v_mfma_f32_16x16x32_bf16 v[58:61], v[138:141], v[162:165], v[58:61]
	v_mfma_f32_16x16x32_bf16 v[54:57], v[130:133], v[170:173], v[54:57]
	v_mfma_f32_16x16x32_bf16 v[50:53], v[138:141], v[170:173], v[50:53]
	v_mfma_f32_16x16x32_bf16 v[46:49], v[130:133], v[178:181], v[46:49]
	v_mfma_f32_16x16x32_bf16 v[42:45], v[138:141], v[178:181], v[42:45]
	v_mfma_f32_16x16x32_bf16 v[38:41], v[130:133], v[186:189], v[38:41]
	v_mfma_f32_16x16x32_bf16 v[34:37], v[138:141], v[186:189], v[34:37]
	v_mfma_f32_16x16x32_bf16 v[62:65], v[134:137], v[166:169], v[62:65]
	v_mfma_f32_16x16x32_bf16 v[58:61], v[142:145], v[166:169], v[58:61]
	v_mfma_f32_16x16x32_bf16 v[54:57], v[134:137], v[174:177], v[54:57]
	v_mfma_f32_16x16x32_bf16 v[50:53], v[142:145], v[174:177], v[50:53]
	v_mfma_f32_16x16x32_bf16 v[46:49], v[134:137], v[182:185], v[46:49]
	v_mfma_f32_16x16x32_bf16 v[42:45], v[142:145], v[182:185], v[42:45]
	v_mfma_f32_16x16x32_bf16 v[38:41], v[134:137], v[190:193], v[38:41]
	v_mfma_f32_16x16x32_bf16 v[34:37], v[142:145], v[190:193], v[34:37]
	v_mfma_f32_16x16x32_bf16 v[30:33], v[146:149], v[162:165], v[30:33]
	v_mfma_f32_16x16x32_bf16 v[26:29], v[154:157], v[162:165], v[26:29]
	v_mfma_f32_16x16x32_bf16 v[22:25], v[146:149], v[170:173], v[22:25]
	v_mfma_f32_16x16x32_bf16 v[18:21], v[154:157], v[170:173], v[18:21]
	v_mfma_f32_16x16x32_bf16 v[14:17], v[146:149], v[178:181], v[14:17]
	v_mfma_f32_16x16x32_bf16 v[10:13], v[154:157], v[178:181], v[10:13]
	v_mfma_f32_16x16x32_bf16 v[6:9], v[146:149], v[186:189], v[6:9]
	v_mfma_f32_16x16x32_bf16 v[2:5], v[154:157], v[186:189], v[2:5]
	v_mfma_f32_16x16x32_bf16 v[30:33], v[150:153], v[166:169], v[30:33]
	v_mfma_f32_16x16x32_bf16 v[26:29], v[158:161], v[166:169], v[26:29]
	v_mfma_f32_16x16x32_bf16 v[22:25], v[150:153], v[174:177], v[22:25]
	v_mfma_f32_16x16x32_bf16 v[18:21], v[158:161], v[174:177], v[18:21]
	v_mfma_f32_16x16x32_bf16 v[14:17], v[150:153], v[182:185], v[14:17]
	v_mfma_f32_16x16x32_bf16 v[10:13], v[158:161], v[182:185], v[10:13]
	v_mfma_f32_16x16x32_bf16 v[6:9], v[150:153], v[190:193], v[6:9]
	v_mfma_f32_16x16x32_bf16 v[2:5], v[158:161], v[190:193], v[2:5]
	s_barrier
	s_setprio 0
	v_add_u32_e32 v0, 0x18000, v230
	ds_read_b128 v[130:133], v0
	ds_read_b128 v[134:137], v0 offset:1024
	ds_read_b128 v[138:141], v0 offset:2048
	ds_read_b128 v[142:145], v0 offset:3072
	v_add_u32_e32 v0, 0x1c000, v230
	ds_read_b128 v[146:149], v0
	ds_read_b128 v[150:153], v0 offset:1024
	ds_read_b128 v[154:157], v0 offset:2048
	ds_read_b128 v[158:161], v0 offset:3072
	s_add_i32 s56, s56, 0x20000
	s_mov_b32 m0, s37
	ds_read_b128 v[162:165], v231 offset:32768
	ds_read_b128 v[166:169], v231 offset:33792
	ds_read_b128 v[170:173], v231 offset:34816
	ds_read_b128 v[174:177], v231 offset:35840
	ds_read_b128 v[178:181], v231 offset:36864
	ds_read_b128 v[182:185], v231 offset:37888
	ds_read_b128 v[186:189], v231 offset:38912
	ds_read_b128 v[190:193], v231 offset:39936
	buffer_load_dwordx4 v199, s[12:15], s56 offen lds
	s_mov_b32 m0, s38
	s_nop 0
	buffer_load_dwordx4 v228, s[12:15], s56 offen lds
	s_waitcnt vmcnt(8)
	s_waitcnt lgkmcnt(0)
	s_setprio 1
	s_barrier
	v_mfma_f32_16x16x32_bf16 v[126:129], v[130:133], v[162:165], v[126:129]
	v_mfma_f32_16x16x32_bf16 v[122:125], v[138:141], v[162:165], v[122:125]
	v_mfma_f32_16x16x32_bf16 v[118:121], v[130:133], v[170:173], v[118:121]
	v_mfma_f32_16x16x32_bf16 v[114:117], v[138:141], v[170:173], v[114:117]
	v_mfma_f32_16x16x32_bf16 v[110:113], v[130:133], v[178:181], v[110:113]
	v_mfma_f32_16x16x32_bf16 v[106:109], v[138:141], v[178:181], v[106:109]
	v_mfma_f32_16x16x32_bf16 v[102:105], v[130:133], v[186:189], v[102:105]
	v_mfma_f32_16x16x32_bf16 v[98:101], v[138:141], v[186:189], v[98:101]
	v_mfma_f32_16x16x32_bf16 v[126:129], v[134:137], v[166:169], v[126:129]
	v_mfma_f32_16x16x32_bf16 v[122:125], v[142:145], v[166:169], v[122:125]
	v_mfma_f32_16x16x32_bf16 v[118:121], v[134:137], v[174:177], v[118:121]
	v_mfma_f32_16x16x32_bf16 v[114:117], v[142:145], v[174:177], v[114:117]
	v_mfma_f32_16x16x32_bf16 v[110:113], v[134:137], v[182:185], v[110:113]
	v_mfma_f32_16x16x32_bf16 v[106:109], v[142:145], v[182:185], v[106:109]
	v_mfma_f32_16x16x32_bf16 v[102:105], v[134:137], v[190:193], v[102:105]
	v_mfma_f32_16x16x32_bf16 v[98:101], v[142:145], v[190:193], v[98:101]
	v_mfma_f32_16x16x32_bf16 v[94:97], v[146:149], v[162:165], v[94:97]
	v_mfma_f32_16x16x32_bf16 v[90:93], v[154:157], v[162:165], v[90:93]
	v_mfma_f32_16x16x32_bf16 v[86:89], v[146:149], v[170:173], v[86:89]
	v_mfma_f32_16x16x32_bf16 v[82:85], v[154:157], v[170:173], v[82:85]
	v_mfma_f32_16x16x32_bf16 v[78:81], v[146:149], v[178:181], v[78:81]
	v_mfma_f32_16x16x32_bf16 v[74:77], v[154:157], v[178:181], v[74:77]
	v_mfma_f32_16x16x32_bf16 v[70:73], v[146:149], v[186:189], v[70:73]
	v_mfma_f32_16x16x32_bf16 v[66:69], v[154:157], v[186:189], v[66:69]
	v_mfma_f32_16x16x32_bf16 v[94:97], v[150:153], v[166:169], v[94:97]
	v_mfma_f32_16x16x32_bf16 v[90:93], v[158:161], v[166:169], v[90:93]
	v_mfma_f32_16x16x32_bf16 v[86:89], v[150:153], v[174:177], v[86:89]
	v_mfma_f32_16x16x32_bf16 v[82:85], v[158:161], v[174:177], v[82:85]
	v_mfma_f32_16x16x32_bf16 v[78:81], v[150:153], v[182:185], v[78:81]
	v_mfma_f32_16x16x32_bf16 v[74:77], v[158:161], v[182:185], v[74:77]
	v_mfma_f32_16x16x32_bf16 v[70:73], v[150:153], v[190:193], v[70:73]
	v_mfma_f32_16x16x32_bf16 v[66:69], v[158:161], v[190:193], v[66:69]
	s_barrier
; template <class Epi, bool ALIGN_EPI, bool SP2, class Hook>
; __device__ __forceinline__ void gemm_phase(LAS unsigned char* lds, const Gemm g, const StaticOrder& S, const Epi& E, Acc& acc, const bool fresh, const Hook& H, const int wave_id) {
;     ...
;         for (int t = t0; t < nt; t += 2) {
;             const bool last = (t == nt - 2);
;             const Src a1 = cA + (size_t)(t + 1) * kstep;
;             const Src a2 = last ? nA : cA + (size_t)(t + 2) * kstep, b2 = last ? nB : cB + (size_t)(t + 2) * kstep;
;             const Src a3 = a2 + kstep, b3 = b2 + kstep;
	s_setprio 0
	s_mov_b32 m0, s39
	ds_read_b128 v[162:165], v231 offset:49152
	ds_read_b128 v[166:169], v231 offset:50176
	ds_read_b128 v[170:173], v231 offset:51200
	ds_read_b128 v[174:177], v231 offset:52224
	ds_read_b128 v[178:181], v231 offset:53248
	ds_read_b128 v[182:185], v231 offset:54272
	ds_read_b128 v[186:189], v231 offset:55296
	ds_read_b128 v[190:193], v231 offset:56320
	buffer_load_dwordx4 v227, s[16:19], s57 offen lds
	s_mov_b32 m0, s40
	s_add_i32 s54, s54, 0x20080
	buffer_load_dwordx4 v229, s[16:19], s57 offen lds
	s_mov_b32 m0, s43
	s_nop 0
	buffer_load_dwordx4 v227, s[16:19], s54 offen lds
	s_mov_b32 m0, s42
	s_nop 0
	buffer_load_dwordx4 v229, s[16:19], s54 offen lds
	s_mov_b32 m0, s41
	s_nop 0
	buffer_load_dwordx4 v199, s[12:15], s21 offen lds
	s_mov_b32 m0, s33
	s_nop 0
	buffer_load_dwordx4 v228, s[12:15], s21 offen lds
	s_waitcnt vmcnt(8)
	s_waitcnt lgkmcnt(0)
	s_setprio 1
	s_barrier
	v_mfma_f32_16x16x32_bf16 v[62:65], v[130:133], v[162:165], v[62:65]
	v_mfma_f32_16x16x32_bf16 v[58:61], v[138:141], v[162:165], v[58:61]
	v_mfma_f32_16x16x32_bf16 v[54:57], v[130:133], v[170:173], v[54:57]
	v_mfma_f32_16x16x32_bf16 v[50:53], v[138:141], v[170:173], v[50:53]
	v_mfma_f32_16x16x32_bf16 v[46:49], v[130:133], v[178:181], v[46:49]
	v_mfma_f32_16x16x32_bf16 v[42:45], v[138:141], v[178:181], v[42:45]
	v_mfma_f32_16x16x32_bf16 v[38:41], v[130:133], v[186:189], v[38:41]
	v_mfma_f32_16x16x32_bf16 v[34:37], v[138:141], v[186:189], v[34:37]
	v_mfma_f32_16x16x32_bf16 v[62:65], v[134:137], v[166:169], v[62:65]
	v_mfma_f32_16x16x32_bf16 v[58:61], v[142:145], v[166:169], v[58:61]
	v_mfma_f32_16x16x32_bf16 v[54:57], v[134:137], v[174:177], v[54:57]
	v_mfma_f32_16x16x32_bf16 v[50:53], v[142:145], v[174:177], v[50:53]
	v_mfma_f32_16x16x32_bf16 v[46:49], v[134:137], v[182:185], v[46:49]
	v_mfma_f32_16x16x32_bf16 v[42:45], v[142:145], v[182:185], v[42:45]
	v_mfma_f32_16x16x32_bf16 v[38:41], v[134:137], v[190:193], v[38:41]
	v_mfma_f32_16x16x32_bf16 v[34:37], v[142:145], v[190:193], v[34:37]
	v_mfma_f32_16x16x32_bf16 v[30:33], v[146:149], v[162:165], v[30:33]
	v_mfma_f32_16x16x32_bf16 v[26:29], v[154:157], v[162:165], v[26:29]
	v_mfma_f32_16x16x32_bf16 v[22:25], v[146:149], v[170:173], v[22:25]
	v_mfma_f32_16x16x32_bf16 v[18:21], v[154:157], v[170:173], v[18:21]
	v_mfma_f32_16x16x32_bf16 v[14:17], v[146:149], v[178:181], v[14:17]
	v_mfma_f32_16x16x32_bf16 v[10:13], v[154:157], v[178:181], v[10:13]
	v_mfma_f32_16x16x32_bf16 v[6:9], v[146:149], v[186:189], v[6:9]
	v_mfma_f32_16x16x32_bf16 v[2:5], v[154:157], v[186:189], v[2:5]
	v_mfma_f32_16x16x32_bf16 v[30:33], v[150:153], v[166:169], v[30:33]
	v_mfma_f32_16x16x32_bf16 v[26:29], v[158:161], v[166:169], v[26:29]
	v_mfma_f32_16x16x32_bf16 v[22:25], v[150:153], v[174:177], v[22:25]
	v_mfma_f32_16x16x32_bf16 v[18:21], v[158:161], v[174:177], v[18:21]
	v_mfma_f32_16x16x32_bf16 v[14:17], v[150:153], v[182:185], v[14:17]
	v_mfma_f32_16x16x32_bf16 v[10:13], v[158:161], v[182:185], v[10:13]
	v_mfma_f32_16x16x32_bf16 v[6:9], v[150:153], v[190:193], v[6:9]
	v_mfma_f32_16x16x32_bf16 v[2:5], v[158:161], v[190:193], v[2:5]
	s_barrier
	s_setprio 0
	s_add_i32 s12, s20, 2
	s_cmp_gt_u32 s20, 5
	s_cbranch_scc1 .LBB0_1032
	s_mov_b32 s20, s12
	s_branch .LBB0_951
